# combo7 + attention: q rows of both query tiles loaded at item start (before K/V staging)
# speedup vs baseline: 1.0026x; 1.0026x over previous
; __device__ __forceinline__ void attn_items(const Params& p, LAS unsigned char* lds, int ai0, int aistride) {
;     ...
;         for (int q = tid; q < nkeys * 8; q += 512) {
;             const int key = q >> 3, d0 = (q & 7) * 8;
;             float kf[8], vf[8]; bool donorm = false;
;             if (!samp || (key >= 128 && key < 144)) {
;                 const int row = samp ? row0 + key - 128 : krow0 + key;
;                 const bf16x8 kr = *(const bf16x8*)(Z + (size_t)row * NZ + ZC_AK + g * 64 + d0), vr = *(const bf16x8*)(Z + (size_t)row * NZ + ZC_AV + g * 64 + d0);
;     ...
;                 const int r = qt / ntt, tok0 = 16 * (qt % ntt), hh = g * 4 + r;
;                 const size_t qrow = (size_t)(row0 + tok0 + fr);
;                 bf16x8 Qf[2];
;                 {
;                     const bf16x8 r0 = *(const bf16x8*)(Z + qrow * NZ + ZC_AQ + hh * 64 + 8 * fq), r1 = *(const bf16x8*)(Z + qrow * NZ + ZC_AQ + hh * 64 + 32 + 8 * fq);
.LBB0_522:
	s_lshl_b32 s46, s60, 3
	s_and_b32 s43, s71, 1
	s_add_i32 s98, s42, -1
	s_ff1_i32_b32 s99, s42
	s_lshl_b32 s100, s43, 2
	v_add_u32_e32 v178, s40, v53
	v_or_b32_e32 v179, 0, v45
	v_lshrrev_b32_e32 v180, s99, v179
	v_and_b32_e32 v179, s98, v179
	v_lshlrev_b32_e32 v179, 4, v179
	v_add_u32_e32 v180, s100, v180
	v_add_u32_e32 v179, v178, v179
	v_mov_b64_e32 v[182:183], s[14:15]
	v_lshl_add_u32 v180, v180, 7, v22
	v_mad_i64_i32 v[182:183], vcc, v179, s68, v[182:183]
	v_mov_b32_e32 v181, 0
	v_lshl_add_u64 v[182:183], v[182:183], 0, v[180:181]
	global_load_dwordx4 v[152:155], v[182:183], off offset:64
	global_load_dwordx4 v[148:151], v[182:183], off
	v_or_b32_e32 v179, 1, v45
	v_lshrrev_b32_e32 v180, s99, v179
	v_and_b32_e32 v179, s98, v179
	v_lshlrev_b32_e32 v179, 4, v179
	v_add_u32_e32 v180, s100, v180
	v_add_u32_e32 v179, v178, v179
	v_mov_b64_e32 v[182:183], s[14:15]
	v_lshl_add_u32 v180, v180, 7, v22
	v_mad_i64_i32 v[182:183], vcc, v179, s68, v[182:183]
	v_mov_b32_e32 v181, 0
	v_lshl_add_u64 v[182:183], v[182:183], 0, v[180:181]
	global_load_dwordx4 v[174:177], v[182:183], off offset:64
	global_load_dwordx4 v[170:173], v[182:183], off
	v_cmp_gt_u32_e32 vcc, s46, v184
	s_and_saveexec_b64 s[8:9], vcc
	s_cbranch_execz .LBB0_543
	s_lshl_b32 s47, s4, 7
	s_lshl_b32 s61, s43, 6
	s_add_i32 s26, s40, 0xffffff80
	s_lshl_b32 s27, s4, 4
	s_cmp_lt_u32 s1, 30
	s_cselect_b64 s[4:5], -1, 0
	s_sub_i32 s62, s60, 64
	s_lshl_b32 s1, s1, 6
	s_and_b64 s[10:11], s[2:3], exec
	s_cselect_b32 s63, s0, s26
	s_lshl_b32 s0, s43, 7
	s_add_u32 s10, s14, s0
	s_addc_u32 s11, s15, 0
	s_add_i32 s0, s47, s1
	s_sub_i32 s0, s0, s60
	s_add_i32 s66, s0, 0xfffff8c0
	s_add_i32 s67, s27, 0xffffff80
	s_mov_b32 s76, 0
	s_mov_b64 s[26:27], 0
	s_xor_b64 s[28:29], s[4:5], -1
	v_mov_b32_e32 v23, v55
	v_mov_b32_e32 v28, v54
	v_mov_b32_e32 v29, v52
	v_mov_b32_e32 v30, v51
	v_mov_b32_e32 v31, v184
	v_add_u32_e32 v36, s63, v44
	v_mov_b64_e32 v[34:35], s[10:11]
	v_and_b32_e32 v37, 56, v52
	s_nop 0
	v_mad_i64_i32 v[34:35], vcc, v36, s68, v[34:35]
	v_lshlrev_b32_e32 v36, 1, v37
	v_mov_b32_e32 v37, 0
	v_lshl_add_u64 v[34:35], v[34:35], 0, v[36:37]
	global_load_dwordx4 v[240:243], v[34:35], off offset:1024
	global_load_dwordx4 v[244:247], v[34:35], off offset:1280
	s_branch .LBB0_525

; __device__ __forceinline__ unsigned cvt_pk_bf16(float lo, float hi) { const f32v2_t v = {lo, hi}; const bf16v2_t r = __builtin_convertvector(v, bf16v2_t); return __builtin_bit_cast(unsigned, r); }
; __device__ __forceinline__ float bf2f(short b) { return __uint_as_float(((unsigned)(unsigned short)b) << 16); }
; __device__ __forceinline__ void attn_items(const Params& p, LAS unsigned char* lds, int ai0, int aistride) {
;     ...
;             if (qt < nqt) {
;                 const int r = qt / ntt, tok0 = 16 * (qt % ntt), hh = g * 4 + r;
;                 const size_t qrow = (size_t)(row0 + tok0 + fr);
;                 bf16x8 Qf[2];
;                 {
;                     const bf16x8 r0 = *(const bf16x8*)(Z + qrow * NZ + ZC_AQ + hh * 64 + 8 * fq), r1 = *(const bf16x8*)(Z + qrow * NZ + ZC_AQ + hh * 64 + 32 + 8 * fq);
;                     float q0[8], q1[8]; float ss = 0.f;
; #pragma unroll
;                     for (int e = 0; e < 8; ++e) { q0[e] = bf2f(r0[e]); q1[e] = bf2f(r1[e]); ss += q0[e] * q0[e] + q1[e] * q1[e]; }
;                     ss += __shfl_xor(ss, 16); ss += __shfl_xor(ss, 32);
;                     const float rq = rsqrtf(ss * (1.0f / 64.0f) + 1e-6f) * 0.125f;
;                     const float4 na = *(const float4*)(p.in[9] + 8 * fq), nb = *(const float4*)(p.in[9] + 8 * fq + 4), nc = *(const float4*)(p.in[9] + 32 + 8 * fq), nd = *(const float4*)(p.in[9] + 32 + 8 * fq + 4);
;                     u32x4 w0, w1;
;                     w0.x = cvt_pk_bf16(q0[0] * rq * na.x, q0[1] * rq * na.y); w0.y = cvt_pk_bf16(q0[2] * rq * na.z, q0[3] * rq * na.w);
;                     w0.z = cvt_pk_bf16(q0[4] * rq * nb.x, q0[5] * rq * nb.y); w0.w = cvt_pk_bf16(q0[6] * rq * nb.z, q0[7] * rq * nb.w);
;                     w1.x = cvt_pk_bf16(q1[0] * rq * nc.x, q1[1] * rq * nc.y); w1.y = cvt_pk_bf16(q1[2] * rq * nc.z, q1[3] * rq * nc.w);
;                     w1.z = cvt_pk_bf16(q1[4] * rq * nd.x, q1[5] * rq * nd.y); w1.w = cvt_pk_bf16(q1[6] * rq * nd.z, q1[7] * rq * nd.w);
;                     Qf[0] = __builtin_bit_cast(bf16x8, w0); Qf[1] = __builtin_bit_cast(bf16x8, w1);
;                 }
;                 const float slope = exp2f(-(float)(hh + 1));
;     ...
;                     const bf16x4 ag = *(const bf16x4*)(Z + qrow * NZ + ZC_AG + hh * 64 + d);
.LBB0_546:
	v_or_b32_e32 v0, s4, v45
	v_cmp_gt_u32_e32 vcc, s76, v0
	s_and_saveexec_b64 s[66:67], vcc
	s_cbranch_execz .LBB0_545
	v_lshrrev_b32_e32 v1, s77, v0
	v_and_b32_e32 v0, s78, v0
	v_lshlrev_b32_e32 v14, 4, v0
	v_add_u32_e32 v28, s79, v1
	v_add_u32_e32 v26, v63, v14
	v_mov_b64_e32 v[0:1], s[14:15]
	v_mad_i64_i32 v[0:1], s[0:1], v26, s68, v[0:1]
	v_lshlrev_b32_e32 v16, 7, v28
	v_lshl_add_u64 v[24:25], v[0:1], 0, v[16:17]
	v_mov_b32_e32 v23, v17
	v_lshl_add_u64 v[4:5], v[24:25], 0, v[22:23]
	s_cmp_eq_u32 s4, 0
	s_cselect_b64 s[100:101], -1, 0
	v_cndmask_b32_e64 v0, v174, v152, s[100:101]
	v_cndmask_b32_e64 v1, v175, v153, s[100:101]
	v_cndmask_b32_e64 v2, v176, v154, s[100:101]
	v_cndmask_b32_e64 v3, v177, v155, s[100:101]
	v_cndmask_b32_e64 v4, v170, v148, s[100:101]
	v_cndmask_b32_e64 v5, v171, v149, s[100:101]
	v_cndmask_b32_e64 v6, v172, v150, s[100:101]
	v_cndmask_b32_e64 v7, v173, v151, s[100:101]
	s_nop 0
	global_load_dwordx4 v[8:11], v[20:21], off offset:144
	global_load_dwordx4 v[30:33], v[20:21], off offset:128
	global_load_dwordx4 v[34:37], v[20:21], off offset:16
	global_load_dwordx4 v[38:41], v[20:21], off
	v_and_b32_e32 v13, 64, v58
	v_xor_b32_e32 v12, 16, v58
	v_add_u32_e32 v13, 64, v13
	v_xor_b32_e32 v15, 32, v58
	v_mov_b32_e32 v29, v17
	v_cmp_lt_i32_e32 vcc, v12, v13
	v_add_u32_e32 v23, 1, v28
	ds_read_b128 v[66:69], v61
	ds_read_b128 v[70:73], v61 offset:64
	ds_read_b128 v[74:77], v61 offset:2304
	ds_read_b128 v[78:81], v61 offset:2368
	v_cndmask_b32_e32 v16, v58, v12, vcc
	v_cmp_lt_i32_e32 vcc, v15, v13
	v_lshl_add_u64 v[12:13], v[28:29], 2, s[74:75]
	v_add_u32_e32 v29, v14, v64
	v_cvt_f32_u32_e32 v14, v23
	global_load_dword v23, v[12:13], off
	v_lshlrev_b32_e32 v27, 2, v16
	v_cndmask_b32_e32 v15, v58, v15, vcc
	v_lshlrev_b32_e32 v16, 2, v15
	v_cmp_lt_f32_e64 s[4:5], s70, v14
	v_sub_u32_e32 v15, v29, v18
	v_lshlrev_b32_e32 v238, 1, v18
	v_mov_b32_e32 v239, 0
	v_lshl_add_u64 v[238:239], v[24:25], 0, v[238:239]
	global_load_dwordx2 v[232:233], v[238:239], off offset:1536
	global_load_dwordx2 v[234:235], v[238:239], off offset:1568
	global_load_dwordx2 v[236:237], v[238:239], off offset:1600
	global_load_dwordx2 v[238:239], v[238:239], off offset:1632
	s_waitcnt vmcnt(0)
	v_and_b32_e32 v43, 0xffff0000, v1
	v_lshlrev_b32_e32 v42, 16, v1
	v_and_b32_e32 v1, 0xffff0000, v0
	v_lshlrev_b32_e32 v0, 16, v0
	v_and_b32_e32 v85, 0xffff0000, v5
	v_lshlrev_b32_e32 v84, 16, v5
	v_and_b32_e32 v5, 0xffff0000, v4
	v_lshlrev_b32_e32 v4, 16, v4
	v_pk_mul_f32 v[92:93], v[0:1], v[0:1]
	v_pk_mul_f32 v[90:91], v[42:43], v[42:43]
	v_pk_fma_f32 v[92:93], v[4:5], v[4:5], v[92:93]
	v_and_b32_e32 v13, 0xffff0000, v3
	v_lshlrev_b32_e32 v12, 16, v3
	v_and_b32_e32 v3, 0xffff0000, v2
	v_lshlrev_b32_e32 v2, 16, v2
	v_pk_fma_f32 v[90:91], v[84:85], v[84:85], v[90:91]
	v_add_f32_e32 v65, v92, v93
	v_and_b32_e32 v83, 0xffff0000, v7
	v_lshlrev_b32_e32 v82, 16, v7
	v_and_b32_e32 v7, 0xffff0000, v6
	v_lshlrev_b32_e32 v6, 16, v6
	v_pk_mul_f32 v[88:89], v[2:3], v[2:3]
	v_add_f32_e32 v65, v90, v65
	v_pk_fma_f32 v[88:89], v[6:7], v[6:7], v[88:89]
	v_add_f32_e32 v65, v91, v65
	v_pk_mul_f32 v[86:87], v[12:13], v[12:13]
	v_add_f32_e32 v65, v88, v65
	v_pk_fma_f32 v[86:87], v[82:83], v[82:83], v[86:87]
	v_add_f32_e32 v65, v89, v65
	v_add_f32_e32 v65, v86, v65
	v_add_f32_e32 v65, v87, v65
	ds_bpermute_b32 v86, v27, v65
	v_add_u32_e32 v87, v29, v46
	v_cvt_f32_i32_e32 v90, v87
	v_add_u32_e32 v87, -2, v15
	v_cvt_f32_i32_e32 v92, v87
	s_waitcnt lgkmcnt(0)
	v_add_f32_e32 v65, v65, v86
	ds_bpermute_b32 v86, v16, v65
	v_add_u32_e32 v91, -3, v15
	v_cvt_f32_i32_e32 v89, v15
	v_sub_u32_e32 v88, v29, v47
	v_cvt_f32_i32_e32 v88, v88
	s_waitcnt lgkmcnt(0)
; #define LAS __attribute__((address_space(3)))
; __device__ __forceinline__ unsigned cvt_pk_bf16(float lo, float hi) { const f32v2_t v = {lo, hi}; const bf16v2_t r = __builtin_convertvector(v, bf16v2_t); return __builtin_bit_cast(unsigned, r); }
; __device__ __forceinline__ void attn_items(const Params& p, LAS unsigned char* lds, int ai0, int aistride) {
;     ...
;                     const float rq = rsqrtf(ss * (1.0f / 64.0f) + 1e-6f) * 0.125f;
;                     const float4 na = *(const float4*)(p.in[9] + 8 * fq), nb = *(const float4*)(p.in[9] + 8 * fq + 4), nc = *(const float4*)(p.in[9] + 32 + 8 * fq), nd = *(const float4*)(p.in[9] + 32 + 8 * fq + 4);
;                     u32x4 w0, w1;
;                     w0.x = cvt_pk_bf16(q0[0] * rq * na.x, q0[1] * rq * na.y); w0.y = cvt_pk_bf16(q0[2] * rq * na.z, q0[3] * rq * na.w);
;                     w0.z = cvt_pk_bf16(q0[4] * rq * nb.x, q0[5] * rq * nb.y); w0.w = cvt_pk_bf16(q0[6] * rq * nb.z, q0[7] * rq * nb.w);
;                     w1.x = cvt_pk_bf16(q1[0] * rq * nc.x, q1[1] * rq * nc.y); w1.y = cvt_pk_bf16(q1[2] * rq * nc.z, q1[3] * rq * nc.w);
;                     w1.z = cvt_pk_bf16(q1[4] * rq * nd.x, q1[5] * rq * nd.y); w1.w = cvt_pk_bf16(q1[6] * rq * nd.z, q1[7] * rq * nd.w);
;                     Qf[0] = __builtin_bit_cast(bf16x8, w0); Qf[1] = __builtin_bit_cast(bf16x8, w1);
;                 }
;                 const float slope = exp2f(-(float)(hh + 1));
;                 const float sink = p.in[11][hh];
;                 const int qoff = samp ? (tok0 + fr + 128) : ((nkc - 1) * 64 + tok0 + fr);
;                 f32x4 s[12]; float mx = sink;
; #pragma unroll
;                 for (int kt = 0; kt < 12; ++kt) {
;                     if (kt < nkt) {
;                         f32x4 acc = {0.f, 0.f, 0.f, 0.f};
; #pragma unroll
;                         for (int kk = 0; kk < 2; ++kk) { const bf16x8 a = *(const LAS bf16x8*)(K_s + (16 * kt + fr) * 72 + 32 * kk + 8 * fq); acc = mfma16(a, Qf[kk], acc); }
; #pragma unroll
;                         for (int jj = 0; jj < 4; ++jj) { const int key = 16 * kt + 4 * fq + jj; const bool valid = !samp || key < 144;
;                             const float sv = valid ? acc[jj] - slope * fabsf((float)(qoff - key)) : -1e30f; s[kt][jj] = sv; mx = fmaxf(mx, sv); }
;                     } else { s[kt] = (f32x4){-1e30f, -1e30f, -1e30f, -1e30f}; }
	v_add_f32_e32 v65, v65, v86
	v_fmamk_f32 v65, v65, 0x3c800000, v57
	v_mul_f32_e32 v86, 0x4b800000, v65
	v_cmp_gt_f32_e32 vcc, s69, v65
	s_nop 1
	v_cndmask_b32_e32 v65, v65, v86, vcc
	v_rsq_f32_e32 v65, v65
	v_cndmask_b32_e64 v86, 0, v59, s[4:5]
	v_sub_f32_e32 v14, v86, v14
	v_exp_f32_e32 v93, v14
	v_mul_f32_e32 v14, 0x45800000, v65
	v_cndmask_b32_e32 v14, v65, v14, vcc
	v_mul_f32_e32 v14, 0x3e000000, v14
	v_pk_mul_f32 v[4:5], v[14:15], v[4:5] op_sel_hi:[0,1]
	v_pk_mul_f32 v[84:85], v[14:15], v[84:85] op_sel_hi:[0,1]
	v_pk_mul_f32 v[6:7], v[14:15], v[6:7] op_sel_hi:[0,1]
	v_pk_mul_f32 v[82:83], v[14:15], v[82:83] op_sel_hi:[0,1]
	v_pk_mul_f32 v[0:1], v[14:15], v[0:1] op_sel_hi:[0,1]
	v_pk_mul_f32 v[86:87], v[14:15], v[2:3] op_sel_hi:[0,1]
	v_pk_mul_f32 v[2:3], v[38:39], v[4:5]
	v_pk_mul_f32 v[4:5], v[40:41], v[84:85]
	v_pk_mul_f32 v[6:7], v[34:35], v[6:7]
	v_pk_mul_f32 v[34:35], v[36:37], v[82:83]
	v_pk_mul_f32 v[42:43], v[14:15], v[42:43] op_sel_hi:[0,1]
	v_pk_mul_f32 v[36:37], v[30:31], v[0:1]
	v_cvt_pk_bf16_f32 v0, v2, v3
	v_cvt_pk_bf16_f32 v1, v4, v5
	v_cvt_pk_bf16_f32 v2, v6, v7
	v_cvt_pk_bf16_f32 v3, v34, v35
	v_pk_mul_f32 v[38:39], v[32:33], v[42:43]
	v_pk_mul_f32 v[12:13], v[14:15], v[12:13] op_sel_hi:[0,1]
	v_mfma_f32_16x16x32_bf16 v[30:33], v[66:69], v[0:3], 0
	v_mul_f32_e64 v6, v8, v86
	v_mul_f32_e64 v7, v9, v87
	v_pk_mul_f32 v[12:13], v[10:11], v[12:13]
	v_cvt_pk_bf16_f32 v4, v36, v37
	v_cvt_pk_bf16_f32 v5, v38, v39
	v_cvt_pk_bf16_f32 v6, v6, v7
	v_cvt_pk_bf16_f32 v7, v12, v13
	v_mfma_f32_16x16x32_bf16 v[8:11], v[74:77], v[0:3], 0
	v_cvt_f32_i32_e32 v12, v91
	v_cndmask_b32_e64 v13, 0, v60, s[4:5]
	v_ldexp_f32 v14, v93, v13
	v_mfma_f32_16x16x32_bf16 v[30:33], v[70:73], v[4:7], v[30:33]
	v_subrev_u32_e32 v34, 19, v15
	v_subrev_u32_e32 v13, 18, v15
	v_cvt_f32_i32_e32 v38, v34
	v_mfma_f32_16x16x32_bf16 v[8:11], v[78:81], v[4:7], v[8:11]
	ds_read_b128 v[34:37], v61 offset:4672
	s_nop 2
	v_fma_f32 v78, -v14, |v89|, v30
	v_fma_f32 v74, -v14, |v90|, v31
	v_fma_f32 v70, -v14, |v92|, v32
	v_fma_f32 v69, -v14, |v12|, v33
	ds_read_b128 v[30:33], v61 offset:4608
	v_subrev_u32_e32 v12, 17, v15
	v_cvt_f32_i32_e32 v12, v12
	v_cvt_f32_i32_e32 v13, v13
	v_fma_f32 v66, -v14, |v88|, v8
	v_max3_f32 v8, v23, v78, v74
	v_max3_f32 v8, v8, v70, v69
	v_fma_f32 v71, -v14, |v12|, v9
	v_max3_f32 v12, v8, v66, v71
	v_fma_f32 v67, -v14, |v13|, v10
	v_fma_f32 v65, -v14, |v38|, v11
	s_waitcnt lgkmcnt(0)
	v_mfma_f32_16x16x32_bf16 v[8:11], v[30:33], v[0:3], 0
	v_sub_u32_e32 v13, v29, v48
	v_cvt_f32_i32_e32 v13, v13
	ds_read_b128 v[30:33], v61 offset:6912
	v_mfma_f32_16x16x32_bf16 v[8:11], v[34:37], v[4:7], v[8:11]
	v_subrev_u32_e32 v34, 35, v15
	v_cvt_f32_i32_e32 v38, v34
	ds_read_b128 v[34:37], v61 offset:6976
	v_max3_f32 v12, v12, v67, v65
	s_andn2_b64 vcc, exec, s[26:27]
	s_nop 2
	v_fma_f32 v68, -v14, |v13|, v8
	v_subrev_u32_e32 v8, 33, v15
	v_subrev_u32_e32 v13, 34, v15
	v_cvt_f32_i32_e32 v8, v8
	v_cvt_f32_i32_e32 v13, v13
	v_fma_f32 v72, -v14, |v38|, v11
	v_fma_f32 v79, -v14, |v8|, v9
	v_fma_f32 v75, -v14, |v13|, v10
	s_waitcnt lgkmcnt(1)
	v_mfma_f32_16x16x32_bf16 v[8:11], v[30:33], v[0:3], 0
	v_sub_u32_e32 v13, v29, v49
	v_cvt_f32_i32_e32 v13, v13
	v_subrev_u32_e32 v29, 51, v15
	s_waitcnt lgkmcnt(0)
	v_mfma_f32_16x16x32_bf16 v[8:11], v[34:37], v[4:7], v[8:11]
	v_cvt_f32_i32_e32 v29, v29
	v_max3_f32 v12, v12, v68, v79
	v_max3_f32 v12, v12, v75, v72
	s_nop 4
	v_fma_f32 v76, -v14, |v13|, v8
	v_subrev_u32_e32 v8, 49, v15
	v_cvt_f32_i32_e32 v8, v8
	v_subrev_u32_e32 v13, 50, v15
	v_cvt_f32_i32_e32 v13, v13
	v_fma_f32 v73, -v14, |v29|, v11
	v_fma_f32 v80, -v14, |v8|, v9
	v_max3_f32 v8, v12, v76, v80
	v_fma_f32 v77, -v14, |v13|, v10
	v_max3_f32 v29, v8, v77, v73
	v_cndmask_b32_e64 v8, 0, 1, s[26:27]
	v_cmp_ne_u32_e64 s[4:5], 1, v8
	v_mov_b32_e32 v8, 0xf149f2ca
	s_cbranch_vccnz .LBB0_550
	ds_read_b128 v[10:13], v61 offset:9216
	ds_read_b128 v[30:33], v61 offset:9280
	v_add_u32_e32 v9, 0xffffffbf, v15
	v_subrev_u32_e32 v34, 64, v15
	v_add_u32_e32 v35, 0xffffffbd, v15
	s_waitcnt lgkmcnt(1)
	v_mfma_f32_16x16x32_bf16 v[10:13], v[10:13], v[0:3], 0
	v_add_u32_e32 v36, 0xffffffbe, v15
	v_cvt_f32_i32_e32 v9, v9
	v_cvt_f32_i32_e32 v34, v34
	v_cvt_f32_i32_e32 v36, v36
	v_cvt_f32_i32_e32 v37, v35
	s_waitcnt lgkmcnt(0)
	v_mfma_f32_16x16x32_bf16 v[30:33], v[30:33], v[4:7], v[10:13]
	v_and_b32_e32 v35, 0x7fffffff, v9
	v_and_b32_e32 v34, 0x7fffffff, v34
	s_nop 0
	v_and_b32_e32 v11, 0x7fffffff, v37
	v_and_b32_e32 v10, 0x7fffffff, v36
	s_nop 2
	v_pk_fma_f32 v[12:13], v[14:15], v[34:35], v[30:31] op_sel_hi:[0,1,1] neg_lo:[1,0,0] neg_hi:[1,0,0]
	v_max3_f32 v9, v29, v12, v13
	v_pk_fma_f32 v[10:11], v[14:15], v[10:11], v[32:33] op_sel_hi:[0,1,1] neg_lo:[1,0,0] neg_hi:[1,0,0]
	v_max3_f32 v29, v9, v10, v11
	s_andn2_b64 vcc, exec, s[28:29]
	s_cbranch_vccz .LBB0_551
